# v13 plus: removed the per-phase s_setprio 1/0 flips in the GEMM1 and GEMM2 8-phase loops
# speedup vs baseline: 1.0074x; 1.0074x over previous
; DI unsigned pk2(float a, float b) { typedef _Float16 h2 __attribute__((ext_vector_type(2))); h2 v; v[0] = (f16)a; v[1] = (f16)b; return __builtin_bit_cast(unsigned, v); }
;   DI void operator()(const f32x4 (&acc)[2][2][4][2], const GUnit& u, int wr, int wc, int fr, int fq) const {
;     ...
; #pragma unroll
;     for (int ai = 0; ai < 2; ++ai)
; #pragma unroll
;       for (int m = 0; m < 4; ++m) {
;         f16* zp = base + (size_t)(row0 + ai * 128 + m * 16) * ld + u.pn * 256 + 32 * wc + 8 * fq;
; #pragma unroll
;         for (int bj = 0; bj < 2; ++bj) {
;           f32x4 v0 = acc[ai][bj][m][0], v1 = acc[ai][bj][m][1];
;           if (seg == 5) { v0 *= QSCALE; v1 *= QSCALE; }
;           u32x4_ w; w.x = pk2(v0[0], v0[1]); w.y = pk2(v0[2], v0[3]); w.z = pk2(v1[0], v1[1]); w.w = pk2(v1[2], v1[3]);
;           __builtin_nontemporal_store(w, (u32x4_*)(zp + bj * 128));
;         }
;       }
.Lpl_skip1:
	s_waitcnt lgkmcnt(8)
	s_barrier
	s_waitcnt lgkmcnt(0)
	s_waitcnt lgkmcnt(0)
	v_mfma_f32_16x16x32_f16 v[58:61], v[130:133], v[170:173], v[58:61]
	v_mfma_f32_16x16x32_f16 v[62:65], v[138:141], v[170:173], v[62:65]
	v_mfma_f32_16x16x32_f16 v[50:53], v[130:133], v[178:181], v[50:53]
	v_mfma_f32_16x16x32_f16 v[54:57], v[138:141], v[178:181], v[54:57]
	v_mfma_f32_16x16x32_f16 v[42:45], v[130:133], v[186:189], v[42:45]
	v_mfma_f32_16x16x32_f16 v[46:49], v[138:141], v[186:189], v[46:49]
	v_mfma_f32_16x16x32_f16 v[26:29], v[130:133], v[194:197], v[26:29]
	v_mfma_f32_16x16x32_f16 v[30:33], v[138:141], v[194:197], v[30:33]
	v_mfma_f32_16x16x32_f16 v[58:61], v[134:137], v[174:177], v[58:61]
	v_mfma_f32_16x16x32_f16 v[62:65], v[142:145], v[174:177], v[62:65]
	v_mfma_f32_16x16x32_f16 v[50:53], v[134:137], v[182:185], v[50:53]
	v_mfma_f32_16x16x32_f16 v[54:57], v[142:145], v[182:185], v[54:57]
	v_mfma_f32_16x16x32_f16 v[42:45], v[134:137], v[190:193], v[42:45]
	v_mfma_f32_16x16x32_f16 v[46:49], v[142:145], v[190:193], v[46:49]
	v_mfma_f32_16x16x32_f16 v[26:29], v[134:137], v[198:201], v[26:29]
	v_mfma_f32_16x16x32_f16 v[30:33], v[142:145], v[198:201], v[30:33]
	s_barrier
	v_or_b32_e32 v162, 0x14000, v168
	s_mov_b32 m0, s54
	v_add_u32_e32 v163, 0x14400, v168
	ds_read_b128 v[202:205], v162
	ds_read_b128 v[206:209], v163
	v_add_u32_e32 v162, 0x14800, v168
	s_add_u32 s96, s46, s30
	v_add_u32_e32 v163, 0x14c00, v168
	ds_read_b128 v[210:213], v162
	ds_read_b128 v[214:217], v163
	global_load_lds_dwordx4 v148, s[46:47]
	s_addc_u32 s97, s47, s31
	s_mov_b32 m0, s55
	v_lshl_add_u64 v[162:163], s[46:47], 0, v[148:149]
	global_load_lds_dwordx4 v148, s[96:97]
	s_barrier
	s_waitcnt lgkmcnt(0)
	v_lshl_add_u64 v[166:167], s[96:97], 0, v[148:149]
	s_waitcnt lgkmcnt(0)
	v_mfma_f32_16x16x32_f16 v[122:125], v[202:205], v[170:173], v[122:125]
	v_mfma_f32_16x16x32_f16 v[126:129], v[210:213], v[170:173], v[126:129]
	v_mfma_f32_16x16x32_f16 v[114:117], v[202:205], v[178:181], v[114:117]
	v_mfma_f32_16x16x32_f16 v[118:121], v[210:213], v[178:181], v[118:121]
	v_mfma_f32_16x16x32_f16 v[106:109], v[202:205], v[186:189], v[106:109]
	v_mfma_f32_16x16x32_f16 v[110:113], v[210:213], v[186:189], v[110:113]
	v_mfma_f32_16x16x32_f16 v[98:101], v[202:205], v[194:197], v[98:101]
	v_mfma_f32_16x16x32_f16 v[102:105], v[210:213], v[194:197], v[102:105]
	v_mfma_f32_16x16x32_f16 v[122:125], v[206:209], v[174:177], v[122:125]
	v_mfma_f32_16x16x32_f16 v[126:129], v[214:217], v[174:177], v[126:129]
	v_mfma_f32_16x16x32_f16 v[114:117], v[206:209], v[182:185], v[114:117]
	v_mfma_f32_16x16x32_f16 v[118:121], v[214:217], v[182:185], v[118:121]
	v_mfma_f32_16x16x32_f16 v[106:109], v[206:209], v[190:193], v[106:109]
	v_mfma_f32_16x16x32_f16 v[110:113], v[214:217], v[190:193], v[110:113]
	v_mfma_f32_16x16x32_f16 v[98:101], v[206:209], v[198:201], v[98:101]
	v_mfma_f32_16x16x32_f16 v[102:105], v[214:217], v[198:201], v[102:105]
	s_mov_b32 m0, s51
	v_lshl_add_u64 v[218:219], s[94:95], 0, v[146:147]
	s_barrier
	s_cmp_lg_u32 s100, 1
	s_cbranch_scc1 .Ldef_A_skip
	s_mov_b64 vcc, 0x30000
	v_cvt_pk_f16_f32 v242, v34, v35
	v_cvt_pk_f16_f32 v243, v36, v37
	v_cvt_pk_f16_f32 v244, v38, v39
	v_cvt_pk_f16_f32 v245, v40, v41
	global_store_dwordx4 v[240:241], v[242:245], off nt
	v_cvt_pk_f16_f32 v246, v18, v19
	v_cvt_pk_f16_f32 v247, v20, v21
	v_cvt_pk_f16_f32 v248, v22, v23
	v_cvt_pk_f16_f32 v249, v24, v25
	v_lshl_add_u64 v[250:251], v[240:241], 0, vcc
	global_store_dwordx4 v[250:251], v[246:249], off nt
	v_cvt_pk_f16_f32 v242, v10, v11
	v_cvt_pk_f16_f32 v243, v12, v13
	v_cvt_pk_f16_f32 v244, v14, v15
	v_cvt_pk_f16_f32 v245, v16, v17
	v_lshl_add_u64 v[252:253], v[250:251], 0, vcc
	global_store_dwordx4 v[252:253], v[242:245], off nt
	v_cvt_pk_f16_f32 v246, v2, v3
	v_cvt_pk_f16_f32 v247, v4, v5
	v_cvt_pk_f16_f32 v248, v6, v7
	v_cvt_pk_f16_f32 v249, v8, v9
	v_lshl_add_u64 v[250:251], v[252:253], 0, vcc
	global_store_dwordx4 v[250:251], v[246:249], off nt
	v_mov_b64_e32 v[2:3], 0
	v_mov_b64_e32 v[4:5], 0
	v_mov_b64_e32 v[6:7], 0
	v_mov_b64_e32 v[8:9], 0
	v_mov_b64_e32 v[10:11], 0
	v_mov_b64_e32 v[12:13], 0
	v_mov_b64_e32 v[14:15], 0
	v_mov_b64_e32 v[16:17], 0
	v_mov_b64_e32 v[18:19], 0
	v_mov_b64_e32 v[20:21], 0
	v_mov_b64_e32 v[22:23], 0
	v_mov_b64_e32 v[24:25], 0
	v_mov_b64_e32 v[34:35], 0
	v_mov_b64_e32 v[36:37], 0
	v_mov_b64_e32 v[38:39], 0
	v_mov_b64_e32 v[40:41], 0
; DI unsigned pk2(float a, float b) { typedef _Float16 h2 __attribute__((ext_vector_type(2))); h2 v; v[0] = (f16)a; v[1] = (f16)b; return __builtin_bit_cast(unsigned, v); }
;   DI void operator()(const f32x4 (&acc)[2][2][4][2], const GUnit& u, int wr, int wc, int fr, int fq) const {
;     ...
; #pragma unroll
;     for (int ai = 0; ai < 2; ++ai)
; #pragma unroll
;       for (int m = 0; m < 4; ++m) {
;         f16* zp = base + (size_t)(row0 + ai * 128 + m * 16) * ld + u.pn * 256 + 32 * wc + 8 * fq;
; #pragma unroll
;         for (int bj = 0; bj < 2; ++bj) {
;           f32x4 v0 = acc[ai][bj][m][0], v1 = acc[ai][bj][m][1];
;           if (seg == 5) { v0 *= QSCALE; v1 *= QSCALE; }
;           u32x4_ w; w.x = pk2(v0[0], v0[1]); w.y = pk2(v0[2], v0[3]); w.z = pk2(v1[0], v1[1]); w.w = pk2(v1[2], v1[3]);
;           __builtin_nontemporal_store(w, (u32x4_*)(zp + bj * 128));
;         }
;       }
.Ldef_A_skip:
	ds_read_b128 v[170:173], v165 offset:16384
	ds_read_b128 v[174:177], v165 offset:17408
	ds_read_b128 v[178:181], v165 offset:18432
	ds_read_b128 v[182:185], v165 offset:19456
	ds_read_b128 v[186:189], v165 offset:20480
	ds_read_b128 v[190:193], v165 offset:21504
	ds_read_b128 v[194:197], v165 offset:22528
	ds_read_b128 v[198:201], v165 offset:23552
	global_load_lds_dwordx4 v[218:219], off
	v_lshl_add_u64 v[220:221], v[218:219], 0, s[0:1]
	s_mov_b32 m0, s56
	s_nop 0
	global_load_lds_dwordx4 v[220:221], off
	s_barrier
	s_waitcnt lgkmcnt(0)
	s_waitcnt lgkmcnt(0)
	v_mfma_f32_16x16x32_f16 v[34:37], v[130:133], v[170:173], v[34:37]
	v_mfma_f32_16x16x32_f16 v[38:41], v[138:141], v[170:173], v[38:41]
	v_mfma_f32_16x16x32_f16 v[18:21], v[130:133], v[178:181], v[18:21]
	v_mfma_f32_16x16x32_f16 v[22:25], v[138:141], v[178:181], v[22:25]
	v_mfma_f32_16x16x32_f16 v[10:13], v[130:133], v[186:189], v[10:13]
	v_mfma_f32_16x16x32_f16 v[14:17], v[138:141], v[186:189], v[14:17]
	v_mfma_f32_16x16x32_f16 v[2:5], v[130:133], v[194:197], v[2:5]
	v_mfma_f32_16x16x32_f16 v[6:9], v[138:141], v[194:197], v[6:9]
	v_mfma_f32_16x16x32_f16 v[34:37], v[134:137], v[174:177], v[34:37]
	v_mfma_f32_16x16x32_f16 v[38:41], v[142:145], v[174:177], v[38:41]
	v_mfma_f32_16x16x32_f16 v[18:21], v[134:137], v[182:185], v[18:21]
	v_mfma_f32_16x16x32_f16 v[22:25], v[142:145], v[182:185], v[22:25]
	v_mfma_f32_16x16x32_f16 v[10:13], v[134:137], v[190:193], v[10:13]
	v_mfma_f32_16x16x32_f16 v[14:17], v[142:145], v[190:193], v[14:17]
	v_mfma_f32_16x16x32_f16 v[2:5], v[134:137], v[198:201], v[2:5]
	v_mfma_f32_16x16x32_f16 v[6:9], v[142:145], v[198:201], v[6:9]
	s_barrier
	s_cmp_lg_u32 s100, 1
	s_cbranch_scc1 .Ldef_B_skip
	s_mov_b64 vcc, 0x30000
	v_cvt_pk_f16_f32 v242, v90, v91
	v_cvt_pk_f16_f32 v243, v92, v93
	v_cvt_pk_f16_f32 v244, v94, v95
	v_cvt_pk_f16_f32 v245, v96, v97
	global_store_dwordx4 v[240:241], v[242:245], off offset:256 nt
	v_cvt_pk_f16_f32 v246, v82, v83
	v_cvt_pk_f16_f32 v247, v84, v85
	v_cvt_pk_f16_f32 v248, v86, v87
	v_cvt_pk_f16_f32 v249, v88, v89
	v_lshl_add_u64 v[250:251], v[240:241], 0, vcc
	global_store_dwordx4 v[250:251], v[246:249], off offset:256 nt
	v_cvt_pk_f16_f32 v242, v74, v75
	v_cvt_pk_f16_f32 v243, v76, v77
	v_cvt_pk_f16_f32 v244, v78, v79
	v_cvt_pk_f16_f32 v245, v80, v81
	v_lshl_add_u64 v[252:253], v[250:251], 0, vcc
	global_store_dwordx4 v[252:253], v[242:245], off offset:256 nt
	v_cvt_pk_f16_f32 v246, v70, v71
	v_cvt_pk_f16_f32 v247, v72, v73
	v_cvt_pk_f16_f32 v248, v66, v67
	v_cvt_pk_f16_f32 v249, v68, v69
	v_lshl_add_u64 v[250:251], v[252:253], 0, vcc
	global_store_dwordx4 v[250:251], v[246:249], off offset:256 nt
	v_mov_b64_e32 v[66:67], 0
	v_mov_b64_e32 v[68:69], 0
	v_mov_b64_e32 v[70:71], 0
	v_mov_b64_e32 v[72:73], 0
	v_mov_b64_e32 v[74:75], 0
	v_mov_b64_e32 v[76:77], 0
	v_mov_b64_e32 v[78:79], 0
	v_mov_b64_e32 v[80:81], 0
	v_mov_b64_e32 v[82:83], 0
	v_mov_b64_e32 v[84:85], 0
	v_mov_b64_e32 v[86:87], 0
	v_mov_b64_e32 v[88:89], 0
	v_mov_b64_e32 v[90:91], 0
	v_mov_b64_e32 v[92:93], 0
	v_mov_b64_e32 v[94:95], 0
	v_mov_b64_e32 v[96:97], 0
	s_mov_b32 s100, 0

.Lpl_wdone:
	s_barrier
	v_mfma_f32_16x16x32_f16 v[90:93], v[202:205], v[170:173], v[90:93]
	v_mfma_f32_16x16x32_f16 v[94:97], v[210:213], v[170:173], v[94:97]
	v_mfma_f32_16x16x32_f16 v[82:85], v[202:205], v[178:181], v[82:85]
	v_mfma_f32_16x16x32_f16 v[86:89], v[210:213], v[178:181], v[86:89]
	v_mfma_f32_16x16x32_f16 v[74:77], v[202:205], v[186:189], v[74:77]
	v_mfma_f32_16x16x32_f16 v[78:81], v[210:213], v[186:189], v[78:81]
	v_mfma_f32_16x16x32_f16 v[70:73], v[202:205], v[194:197], v[70:73]
	v_mfma_f32_16x16x32_f16 v[66:69], v[210:213], v[194:197], v[66:69]
	v_mfma_f32_16x16x32_f16 v[90:93], v[206:209], v[174:177], v[90:93]
	v_mfma_f32_16x16x32_f16 v[94:97], v[214:217], v[174:177], v[94:97]
	v_mfma_f32_16x16x32_f16 v[82:85], v[206:209], v[182:185], v[82:85]
	v_mfma_f32_16x16x32_f16 v[86:89], v[214:217], v[182:185], v[86:89]
	v_mfma_f32_16x16x32_f16 v[74:77], v[206:209], v[190:193], v[74:77]
	v_mfma_f32_16x16x32_f16 v[78:81], v[214:217], v[190:193], v[78:81]
	v_mfma_f32_16x16x32_f16 v[70:73], v[206:209], v[198:201], v[70:73]
	v_mfma_f32_16x16x32_f16 v[66:69], v[214:217], v[198:201], v[66:69]
	v_or_b32_e32 v130, 0x18000, v168
	v_add_u32_e32 v134, 0x18400, v168
	v_add_u32_e32 v138, 0x18800, v168
	v_add_u32_e32 v142, 0x18c00, v168
	s_barrier
	ds_read_b128 v[130:133], v130
	ds_read_b128 v[134:137], v134
	ds_read_b128 v[138:141], v138
	ds_read_b128 v[142:145], v142
	s_mov_b32 m0, s61
	v_lshl_add_u64 v[202:203], v[218:219], 0, s[8:9]
	ds_read_b128 v[170:173], v165 offset:32768
	ds_read_b128 v[174:177], v165 offset:33792
	ds_read_b128 v[178:181], v165 offset:34816
	ds_read_b128 v[182:185], v165 offset:35840
	ds_read_b128 v[186:189], v165 offset:36864
	ds_read_b128 v[190:193], v165 offset:37888
	ds_read_b128 v[194:197], v165 offset:38912
	ds_read_b128 v[198:201], v165 offset:39936
	global_load_lds_dwordx4 v[202:203], off
	v_lshl_add_u64 v[202:203], v[218:219], 0, s[12:13]
	s_mov_b32 m0, s62
	s_nop 0
	global_load_lds_dwordx4 v[202:203], off
	s_waitcnt lgkmcnt(8)
	s_barrier
	s_waitcnt lgkmcnt(0)
	s_waitcnt lgkmcnt(0)
	v_mfma_f32_16x16x32_f16 v[58:61], v[130:133], v[170:173], v[58:61]
	v_mfma_f32_16x16x32_f16 v[62:65], v[138:141], v[170:173], v[62:65]
	v_mfma_f32_16x16x32_f16 v[50:53], v[130:133], v[178:181], v[50:53]
	v_mfma_f32_16x16x32_f16 v[54:57], v[138:141], v[178:181], v[54:57]
	v_mfma_f32_16x16x32_f16 v[42:45], v[130:133], v[186:189], v[42:45]
	v_mfma_f32_16x16x32_f16 v[46:49], v[138:141], v[186:189], v[46:49]
	v_mfma_f32_16x16x32_f16 v[26:29], v[130:133], v[194:197], v[26:29]
	v_mfma_f32_16x16x32_f16 v[30:33], v[138:141], v[194:197], v[30:33]
	v_mfma_f32_16x16x32_f16 v[58:61], v[134:137], v[174:177], v[58:61]
	v_mfma_f32_16x16x32_f16 v[62:65], v[142:145], v[174:177], v[62:65]
	v_mfma_f32_16x16x32_f16 v[50:53], v[134:137], v[182:185], v[50:53]
	v_mfma_f32_16x16x32_f16 v[54:57], v[142:145], v[182:185], v[54:57]
	v_mfma_f32_16x16x32_f16 v[42:45], v[134:137], v[190:193], v[42:45]
	v_mfma_f32_16x16x32_f16 v[46:49], v[142:145], v[190:193], v[46:49]
	v_mfma_f32_16x16x32_f16 v[26:29], v[134:137], v[198:201], v[26:29]
	v_mfma_f32_16x16x32_f16 v[30:33], v[142:145], v[198:201], v[30:33]
	s_barrier
	v_or_b32_e32 v164, 0x1c000, v168
	v_add_u32_e32 v206, 0x1c400, v168
	s_mov_b32 m0, s63
	ds_read_b128 v[202:205], v164
	ds_read_b128 v[206:209], v206
	v_add_u32_e32 v164, 0x1c800, v168
	v_add_u32_e32 v214, 0x1cc00, v168
	v_lshl_add_u64 v[162:163], v[162:163], 0, s[14:15]
	ds_read_b128 v[210:213], v164
	ds_read_b128 v[214:217], v214
	global_load_lds_dwordx4 v[162:163], off
	v_lshl_add_u64 v[162:163], v[166:167], 0, s[14:15]
	s_mov_b32 m0, s64
	s_nop 0
	global_load_lds_dwordx4 v[162:163], off
	s_barrier
; template <bool PEEL, class Sched, class Epi>
; DI void gemm_stream(LAS unsigned char* lds, int K, long lda, long ldb, const Sched& S, const Epi& E) {
;     ...
;     if (PEEL) { GS_TRIP(0, 1); for (int t = 2; t < nt; t += 2) { GS_TRIP(t, 0); } }
;     else { for (int t = 0; t < nt; t += 2) { GS_TRIP(t, 0); } }
	s_waitcnt lgkmcnt(0)
	s_waitcnt lgkmcnt(0)
	v_mfma_f32_16x16x32_f16 v[122:125], v[202:205], v[170:173], v[122:125]
	v_mfma_f32_16x16x32_f16 v[126:129], v[210:213], v[170:173], v[126:129]
	v_mfma_f32_16x16x32_f16 v[114:117], v[202:205], v[178:181], v[114:117]
	v_mfma_f32_16x16x32_f16 v[118:121], v[210:213], v[178:181], v[118:121]
	v_mfma_f32_16x16x32_f16 v[106:109], v[202:205], v[186:189], v[106:109]
	v_mfma_f32_16x16x32_f16 v[110:113], v[210:213], v[186:189], v[110:113]
	v_mfma_f32_16x16x32_f16 v[98:101], v[202:205], v[194:197], v[98:101]
	v_mfma_f32_16x16x32_f16 v[102:105], v[210:213], v[194:197], v[102:105]
	v_mfma_f32_16x16x32_f16 v[122:125], v[206:209], v[174:177], v[122:125]
	v_mfma_f32_16x16x32_f16 v[126:129], v[214:217], v[174:177], v[126:129]
	v_mfma_f32_16x16x32_f16 v[114:117], v[206:209], v[182:185], v[114:117]
	v_mfma_f32_16x16x32_f16 v[118:121], v[214:217], v[182:185], v[118:121]
	v_mfma_f32_16x16x32_f16 v[106:109], v[206:209], v[190:193], v[106:109]
	v_mfma_f32_16x16x32_f16 v[110:113], v[214:217], v[190:193], v[110:113]
	v_mfma_f32_16x16x32_f16 v[98:101], v[206:209], v[198:201], v[98:101]
	v_mfma_f32_16x16x32_f16 v[102:105], v[214:217], v[198:201], v[102:105]
	s_mov_b32 m0, s65
	v_lshl_add_u64 v[162:163], v[218:219], 0, s[14:15]
	s_barrier
	ds_read_b128 v[170:173], v165 offset:49152
	ds_read_b128 v[174:177], v165 offset:50176
	ds_read_b128 v[178:181], v165 offset:51200
	ds_read_b128 v[182:185], v165 offset:52224
	ds_read_b128 v[186:189], v165 offset:53248
	ds_read_b128 v[190:193], v165 offset:54272
	ds_read_b128 v[194:197], v165 offset:55296
	ds_read_b128 v[198:201], v165 offset:56320
	global_load_lds_dwordx4 v[162:163], off
	v_lshl_add_u64 v[162:163], v[218:219], 0, s[16:17]
	s_mov_b32 m0, s72
	s_nop 0
	global_load_lds_dwordx4 v[162:163], off
	s_barrier
	s_waitcnt lgkmcnt(0)
	s_waitcnt lgkmcnt(0)
	v_mfma_f32_16x16x32_f16 v[34:37], v[130:133], v[170:173], v[34:37]
	v_mfma_f32_16x16x32_f16 v[38:41], v[138:141], v[170:173], v[38:41]
	v_mfma_f32_16x16x32_f16 v[18:21], v[130:133], v[178:181], v[18:21]
	v_mfma_f32_16x16x32_f16 v[22:25], v[138:141], v[178:181], v[22:25]
	v_mfma_f32_16x16x32_f16 v[10:13], v[130:133], v[186:189], v[10:13]
	v_mfma_f32_16x16x32_f16 v[14:17], v[138:141], v[186:189], v[14:17]
	v_mfma_f32_16x16x32_f16 v[2:5], v[130:133], v[194:197], v[2:5]
	v_mfma_f32_16x16x32_f16 v[6:9], v[138:141], v[194:197], v[6:9]
	v_mfma_f32_16x16x32_f16 v[34:37], v[134:137], v[174:177], v[34:37]
	v_mfma_f32_16x16x32_f16 v[38:41], v[142:145], v[174:177], v[38:41]
	v_mfma_f32_16x16x32_f16 v[18:21], v[134:137], v[182:185], v[18:21]
	v_mfma_f32_16x16x32_f16 v[22:25], v[142:145], v[182:185], v[22:25]
	v_mfma_f32_16x16x32_f16 v[10:13], v[134:137], v[190:193], v[10:13]
	v_mfma_f32_16x16x32_f16 v[14:17], v[142:145], v[190:193], v[14:17]
	v_mfma_f32_16x16x32_f16 v[2:5], v[134:137], v[198:201], v[2:5]
	v_mfma_f32_16x16x32_f16 v[6:9], v[142:145], v[198:201], v[6:9]
	s_barrier
	s_mov_b32 m0, s73
	v_lshl_add_u64 v[130:131], v[220:221], 0, s[14:15]
	global_load_lds_dwordx4 v[130:131], off
	v_lshl_add_u64 v[130:131], v[222:223], 0, s[14:15]
	s_mov_b32 m0, s74
	s_nop 0
	global_load_lds_dwordx4 v[130:131], off
	s_waitcnt vmcnt(6)
	s_barrier
	s_cmp_lg_u32 s93, 12
	s_cbranch_scc1 .Lpl_skip8
	s_and_b64 vcc, exec, s[6:7]
	s_cbranch_vccz .Lpl_skip8
	s_add_u32 s94, s43, 0x40080
	s_addc_u32 s95, s29, 0
	s_mov_b32 m0, s79
	v_lshl_add_u64 v[130:131], s[94:95], 0, v[160:161]
	global_load_lds_dwordx4 v[130:131], off
	v_lshl_add_u64 v[130:131], v[130:131], 0, s[0:1]
	s_mov_b32 m0, s80
	s_nop 0
	global_load_lds_dwordx4 v[130:131], off
.Lpl_skip8:
	v_mfma_f32_16x16x32_f16 v[90:93], v[202:205], v[170:173], v[90:93]
	v_mfma_f32_16x16x32_f16 v[94:97], v[210:213], v[170:173], v[94:97]
	v_mfma_f32_16x16x32_f16 v[82:85], v[202:205], v[178:181], v[82:85]
	v_mfma_f32_16x16x32_f16 v[86:89], v[210:213], v[178:181], v[86:89]
	v_mfma_f32_16x16x32_f16 v[74:77], v[202:205], v[186:189], v[74:77]
	v_mfma_f32_16x16x32_f16 v[78:81], v[210:213], v[186:189], v[78:81]
	v_mfma_f32_16x16x32_f16 v[70:73], v[202:205], v[194:197], v[70:73]
	v_mfma_f32_16x16x32_f16 v[66:69], v[210:213], v[194:197], v[66:69]
	v_mfma_f32_16x16x32_f16 v[90:93], v[206:209], v[174:177], v[90:93]
	v_mfma_f32_16x16x32_f16 v[94:97], v[214:217], v[174:177], v[94:97]
	v_mfma_f32_16x16x32_f16 v[82:85], v[206:209], v[182:185], v[82:85]
	v_mfma_f32_16x16x32_f16 v[86:89], v[214:217], v[182:185], v[86:89]
	v_mfma_f32_16x16x32_f16 v[74:77], v[206:209], v[190:193], v[74:77]
	v_mfma_f32_16x16x32_f16 v[78:81], v[214:217], v[190:193], v[78:81]
	v_mfma_f32_16x16x32_f16 v[70:73], v[206:209], v[198:201], v[70:73]
	v_mfma_f32_16x16x32_f16 v[66:69], v[214:217], v[198:201], v[66:69]
	s_add_i32 s93, s93, 2
	s_add_u32 s44, s44, 0x100
	s_addc_u32 s45, s45, 0
	s_add_u32 s91, s91, 0x100
	s_addc_u32 s92, s92, 0
	s_cmp_gt_u32 s93, 13
	s_barrier
	s_cbranch_scc1 .LBB0_264

.LBB0_843:
	v_or_b32_e32 v136, 0x10000, v142
	v_add_u32_e32 v144, 0x10400, v142
	v_add_u32_e32 v148, 0x10800, v142
	v_add_u32_e32 v152, 0x10c00, v142
	ds_read_b128 v[136:139], v136
	ds_read_b128 v[144:147], v144
	ds_read_b128 v[148:151], v148
	ds_read_b128 v[152:155], v152
	s_add_u32 s86, s44, 0xffe80080
	s_addc_u32 s87, s45, -1
	s_and_b64 s[46:47], s[46:47], exec
	s_cselect_b32 s47, s4, s87
	s_cselect_b32 s46, s43, s86
	s_cselect_b32 s87, s48, s84
	s_cselect_b32 s86, s50, s51
	s_mov_b32 m0, s79
	v_lshl_add_u64 v[188:189], s[44:45], 0, v[134:135]
	ds_read_b128 v[156:159], v141
	ds_read_b128 v[160:163], v141 offset:1024
	ds_read_b128 v[164:167], v141 offset:2048
	ds_read_b128 v[168:171], v141 offset:3072
	ds_read_b128 v[172:175], v141 offset:4096
	ds_read_b128 v[176:179], v141 offset:5120
	ds_read_b128 v[180:183], v141 offset:6144
	ds_read_b128 v[184:187], v141 offset:7168
	global_load_lds_dwordx4 v[188:189], off
	v_lshl_add_u64 v[188:189], v[188:189], 0, s[16:17]
	s_mov_b32 m0, s80
	s_nop 0
	global_load_lds_dwordx4 v[188:189], off
	s_waitcnt lgkmcnt(8)
	s_barrier
	s_waitcnt lgkmcnt(0)
	s_waitcnt lgkmcnt(0)
	v_mfma_f32_16x16x32_f16 v[118:121], v[136:139], v[156:159], v[118:121]
	v_mfma_f32_16x16x32_f16 v[114:117], v[148:151], v[156:159], v[114:117]
	v_mfma_f32_16x16x32_f16 v[102:105], v[136:139], v[164:167], v[102:105]
	v_mfma_f32_16x16x32_f16 v[98:101], v[148:151], v[164:167], v[98:101]
	v_mfma_f32_16x16x32_f16 v[86:89], v[136:139], v[172:175], v[86:89]
	v_mfma_f32_16x16x32_f16 v[82:85], v[148:151], v[172:175], v[82:85]
	v_mfma_f32_16x16x32_f16 v[66:69], v[136:139], v[180:183], v[66:69]
	v_mfma_f32_16x16x32_f16 v[54:57], v[148:151], v[180:183], v[54:57]
	v_mfma_f32_16x16x32_f16 v[118:121], v[144:147], v[160:163], v[118:121]
	v_mfma_f32_16x16x32_f16 v[114:117], v[152:155], v[160:163], v[114:117]
	v_mfma_f32_16x16x32_f16 v[102:105], v[144:147], v[168:171], v[102:105]
	v_mfma_f32_16x16x32_f16 v[98:101], v[152:155], v[168:171], v[98:101]
	v_mfma_f32_16x16x32_f16 v[86:89], v[144:147], v[176:179], v[86:89]
	v_mfma_f32_16x16x32_f16 v[82:85], v[152:155], v[176:179], v[82:85]
	v_mfma_f32_16x16x32_f16 v[66:69], v[144:147], v[184:187], v[66:69]
	v_mfma_f32_16x16x32_f16 v[54:57], v[152:155], v[184:187], v[54:57]
	s_barrier
	s_mov_b32 m0, s57
	v_or_b32_e32 v188, 0x14000, v142
	v_add_u32_e32 v192, 0x14400, v142
	v_add_u32_e32 v196, 0x14800, v142
	v_add_u32_e32 v200, 0x14c00, v142
	v_lshl_add_u64 v[204:205], s[86:87], 0, v[132:133]
	ds_read_b128 v[188:191], v188
	ds_read_b128 v[192:195], v192
	ds_read_b128 v[196:199], v196
	ds_read_b128 v[200:203], v200
	global_load_lds_dwordx4 v132, s[86:87]
	v_lshl_add_u64 v[206:207], v[204:205], 0, s[14:15]
	s_mov_b32 m0, s58
	s_nop 0
	global_load_lds_dwordx4 v[206:207], off
	s_barrier
	s_waitcnt lgkmcnt(0)
	s_waitcnt lgkmcnt(0)
	v_mfma_f32_16x16x32_f16 v[122:125], v[188:191], v[156:159], v[122:125]
	v_mfma_f32_16x16x32_f16 v[126:129], v[196:199], v[156:159], v[126:129]
	v_mfma_f32_16x16x32_f16 v[106:109], v[188:191], v[164:167], v[106:109]
	v_mfma_f32_16x16x32_f16 v[110:113], v[196:199], v[164:167], v[110:113]
	v_mfma_f32_16x16x32_f16 v[90:93], v[188:191], v[172:175], v[90:93]
	v_mfma_f32_16x16x32_f16 v[94:97], v[196:199], v[172:175], v[94:97]
	v_mfma_f32_16x16x32_f16 v[74:77], v[188:191], v[180:183], v[74:77]
	v_mfma_f32_16x16x32_f16 v[78:81], v[196:199], v[180:183], v[78:81]
	v_mfma_f32_16x16x32_f16 v[122:125], v[192:195], v[160:163], v[122:125]
	v_mfma_f32_16x16x32_f16 v[126:129], v[200:203], v[160:163], v[126:129]
	v_mfma_f32_16x16x32_f16 v[106:109], v[192:195], v[168:171], v[106:109]
	v_mfma_f32_16x16x32_f16 v[110:113], v[200:203], v[168:171], v[110:113]
	v_mfma_f32_16x16x32_f16 v[90:93], v[192:195], v[176:179], v[90:93]
	v_mfma_f32_16x16x32_f16 v[94:97], v[200:203], v[176:179], v[94:97]
	v_mfma_f32_16x16x32_f16 v[74:77], v[192:195], v[184:187], v[74:77]
	v_mfma_f32_16x16x32_f16 v[78:81], v[200:203], v[184:187], v[78:81]
	s_mov_b32 m0, s56
	v_lshl_add_u64 v[206:207], s[46:47], 0, v[130:131]
	s_barrier
	ds_read_b128 v[156:159], v141 offset:16384
	ds_read_b128 v[160:163], v141 offset:17408
	ds_read_b128 v[164:167], v141 offset:18432
	ds_read_b128 v[168:171], v141 offset:19456
	ds_read_b128 v[172:175], v141 offset:20480
	ds_read_b128 v[176:179], v141 offset:21504
	ds_read_b128 v[180:183], v141 offset:22528
	ds_read_b128 v[184:187], v141 offset:23552
	global_load_lds_dwordx4 v[206:207], off
	v_lshl_add_u64 v[208:209], v[206:207], 0, s[16:17]
	s_mov_b32 m0, s59
	s_nop 0
	global_load_lds_dwordx4 v[208:209], off
	s_barrier
	s_waitcnt lgkmcnt(0)
	s_waitcnt lgkmcnt(0)
	v_mfma_f32_16x16x32_f16 v[58:61], v[136:139], v[156:159], v[58:61]
	v_mfma_f32_16x16x32_f16 v[50:53], v[148:151], v[156:159], v[50:53]
	v_mfma_f32_16x16x32_f16 v[38:41], v[136:139], v[164:167], v[38:41]
	v_mfma_f32_16x16x32_f16 v[34:37], v[148:151], v[164:167], v[34:37]
	v_mfma_f32_16x16x32_f16 v[22:25], v[136:139], v[172:175], v[22:25]
	v_mfma_f32_16x16x32_f16 v[18:21], v[148:151], v[172:175], v[18:21]
	v_mfma_f32_16x16x32_f16 v[10:13], v[136:139], v[180:183], v[10:13]
	v_mfma_f32_16x16x32_f16 v[6:9], v[148:151], v[180:183], v[6:9]
	v_mfma_f32_16x16x32_f16 v[58:61], v[144:147], v[160:163], v[58:61]
	v_mfma_f32_16x16x32_f16 v[50:53], v[152:155], v[160:163], v[50:53]
	v_mfma_f32_16x16x32_f16 v[38:41], v[144:147], v[168:171], v[38:41]
	v_mfma_f32_16x16x32_f16 v[34:37], v[152:155], v[168:171], v[34:37]
	v_mfma_f32_16x16x32_f16 v[22:25], v[144:147], v[176:179], v[22:25]
	v_mfma_f32_16x16x32_f16 v[18:21], v[152:155], v[176:179], v[18:21]
	v_mfma_f32_16x16x32_f16 v[10:13], v[144:147], v[184:187], v[10:13]
	v_mfma_f32_16x16x32_f16 v[6:9], v[152:155], v[184:187], v[6:9]
	s_barrier
	s_mov_b32 m0, s60
	v_lshl_add_u64 v[136:137], v[204:205], 0, s[18:19]
	global_load_lds_dwordx4 v[136:137], off
	v_lshl_add_u64 v[136:137], v[204:205], 0, s[16:17]
	s_mov_b32 m0, s61
	s_nop 0
	global_load_lds_dwordx4 v[136:137], off
	s_waitcnt vmcnt(6)
	s_barrier
	v_mfma_f32_16x16x32_f16 v[62:65], v[188:191], v[156:159], v[62:65]
	v_mfma_f32_16x16x32_f16 v[70:73], v[196:199], v[156:159], v[70:73]
	v_mfma_f32_16x16x32_f16 v[42:45], v[188:191], v[164:167], v[42:45]
	v_mfma_f32_16x16x32_f16 v[46:49], v[196:199], v[164:167], v[46:49]
	v_mfma_f32_16x16x32_f16 v[26:29], v[188:191], v[172:175], v[26:29]
	v_mfma_f32_16x16x32_f16 v[30:33], v[196:199], v[172:175], v[30:33]
	v_mfma_f32_16x16x32_f16 v[14:17], v[188:191], v[180:183], v[14:17]
	v_mfma_f32_16x16x32_f16 v[2:5], v[196:199], v[180:183], v[2:5]
	v_mfma_f32_16x16x32_f16 v[62:65], v[192:195], v[160:163], v[62:65]
	v_mfma_f32_16x16x32_f16 v[70:73], v[200:203], v[160:163], v[70:73]
	v_mfma_f32_16x16x32_f16 v[42:45], v[192:195], v[168:171], v[42:45]
	v_mfma_f32_16x16x32_f16 v[46:49], v[200:203], v[168:171], v[46:49]
	v_mfma_f32_16x16x32_f16 v[26:29], v[192:195], v[176:179], v[26:29]
	v_mfma_f32_16x16x32_f16 v[30:33], v[200:203], v[176:179], v[30:33]
	v_mfma_f32_16x16x32_f16 v[14:17], v[192:195], v[184:187], v[14:17]
	v_mfma_f32_16x16x32_f16 v[2:5], v[200:203], v[184:187], v[2:5]
	v_or_b32_e32 v136, 0x18000, v142
	v_add_u32_e32 v144, 0x18400, v142
	v_add_u32_e32 v148, 0x18800, v142
	v_add_u32_e32 v152, 0x18c00, v142
	s_barrier
	ds_read_b128 v[136:139], v136
	ds_read_b128 v[144:147], v144
	ds_read_b128 v[148:151], v148
	ds_read_b128 v[152:155], v152
	s_mov_b32 m0, s62
	v_lshl_add_u64 v[188:189], v[206:207], 0, s[20:21]
	ds_read_b128 v[156:159], v141 offset:32768
	ds_read_b128 v[160:163], v141 offset:33792
	ds_read_b128 v[164:167], v141 offset:34816
	ds_read_b128 v[168:171], v141 offset:35840
	ds_read_b128 v[172:175], v141 offset:36864
	ds_read_b128 v[176:179], v141 offset:37888
	ds_read_b128 v[180:183], v141 offset:38912
	ds_read_b128 v[184:187], v141 offset:39936
	global_load_lds_dwordx4 v[188:189], off
	v_lshl_add_u64 v[188:189], v[206:207], 0, s[22:23]
	s_mov_b32 m0, s63
	s_nop 0
	global_load_lds_dwordx4 v[188:189], off
	s_waitcnt lgkmcnt(8)
	s_barrier
	s_waitcnt lgkmcnt(0)
	s_waitcnt lgkmcnt(0)
	v_mfma_f32_16x16x32_f16 v[118:121], v[136:139], v[156:159], v[118:121]
	v_mfma_f32_16x16x32_f16 v[114:117], v[148:151], v[156:159], v[114:117]
	v_mfma_f32_16x16x32_f16 v[102:105], v[136:139], v[164:167], v[102:105]
	v_mfma_f32_16x16x32_f16 v[98:101], v[148:151], v[164:167], v[98:101]
	v_mfma_f32_16x16x32_f16 v[86:89], v[136:139], v[172:175], v[86:89]
	v_mfma_f32_16x16x32_f16 v[82:85], v[148:151], v[172:175], v[82:85]
	v_mfma_f32_16x16x32_f16 v[66:69], v[136:139], v[180:183], v[66:69]
	v_mfma_f32_16x16x32_f16 v[54:57], v[148:151], v[180:183], v[54:57]
	v_mfma_f32_16x16x32_f16 v[118:121], v[144:147], v[160:163], v[118:121]
	v_mfma_f32_16x16x32_f16 v[114:117], v[152:155], v[160:163], v[114:117]
	v_mfma_f32_16x16x32_f16 v[102:105], v[144:147], v[168:171], v[102:105]
	v_mfma_f32_16x16x32_f16 v[98:101], v[152:155], v[168:171], v[98:101]
	v_mfma_f32_16x16x32_f16 v[86:89], v[144:147], v[176:179], v[86:89]
	v_mfma_f32_16x16x32_f16 v[82:85], v[152:155], v[176:179], v[82:85]
	v_mfma_f32_16x16x32_f16 v[66:69], v[144:147], v[184:187], v[66:69]
	v_mfma_f32_16x16x32_f16 v[54:57], v[152:155], v[184:187], v[54:57]
	s_barrier
	s_mov_b32 m0, s64
	v_or_b32_e32 v188, 0x1c000, v142
	v_add_u32_e32 v192, 0x1c400, v142
	v_add_u32_e32 v196, 0x1c800, v142
	v_add_u32_e32 v200, 0x1cc00, v142
	v_lshl_add_u64 v[208:209], v[204:205], 0, s[24:25]
	ds_read_b128 v[188:191], v188
	ds_read_b128 v[192:195], v192
	ds_read_b128 v[196:199], v196
	ds_read_b128 v[200:203], v200
	global_load_lds_dwordx4 v[208:209], off
	v_lshl_add_u64 v[208:209], v[204:205], 0, s[26:27]
	s_mov_b32 m0, s65
	s_nop 0
	global_load_lds_dwordx4 v[208:209], off
	s_barrier
; template <bool PEEL, class Sched, class Epi>
; DI void gemm_stream(LAS unsigned char* lds, int K, long lda, long ldb, const Sched& S, const Epi& E) {
;     ...
;     if (PEEL) { GS_TRIP(0, 1); for (int t = 2; t < nt; t += 2) { GS_TRIP(t, 0); } }
;     else { for (int t = 0; t < nt; t += 2) { GS_TRIP(t, 0); } }
	s_waitcnt lgkmcnt(0)
	s_waitcnt lgkmcnt(0)
	v_mfma_f32_16x16x32_f16 v[122:125], v[188:191], v[156:159], v[122:125]
	v_mfma_f32_16x16x32_f16 v[126:129], v[196:199], v[156:159], v[126:129]
	v_mfma_f32_16x16x32_f16 v[106:109], v[188:191], v[164:167], v[106:109]
	v_mfma_f32_16x16x32_f16 v[110:113], v[196:199], v[164:167], v[110:113]
	v_mfma_f32_16x16x32_f16 v[90:93], v[188:191], v[172:175], v[90:93]
	v_mfma_f32_16x16x32_f16 v[94:97], v[196:199], v[172:175], v[94:97]
	v_mfma_f32_16x16x32_f16 v[74:77], v[188:191], v[180:183], v[74:77]
	v_mfma_f32_16x16x32_f16 v[78:81], v[196:199], v[180:183], v[78:81]
	v_mfma_f32_16x16x32_f16 v[122:125], v[192:195], v[160:163], v[122:125]
	v_mfma_f32_16x16x32_f16 v[126:129], v[200:203], v[160:163], v[126:129]
	v_mfma_f32_16x16x32_f16 v[106:109], v[192:195], v[168:171], v[106:109]
	v_mfma_f32_16x16x32_f16 v[110:113], v[200:203], v[168:171], v[110:113]
	v_mfma_f32_16x16x32_f16 v[90:93], v[192:195], v[176:179], v[90:93]
	v_mfma_f32_16x16x32_f16 v[94:97], v[200:203], v[176:179], v[94:97]
	v_mfma_f32_16x16x32_f16 v[74:77], v[192:195], v[184:187], v[74:77]
	v_mfma_f32_16x16x32_f16 v[78:81], v[200:203], v[184:187], v[78:81]
	s_mov_b32 m0, s72
	v_lshl_add_u64 v[208:209], v[206:207], 0, s[24:25]
	s_barrier
	ds_read_b128 v[156:159], v141 offset:49152
	ds_read_b128 v[160:163], v141 offset:50176
	ds_read_b128 v[164:167], v141 offset:51200
	ds_read_b128 v[168:171], v141 offset:52224
	ds_read_b128 v[172:175], v141 offset:53248
	ds_read_b128 v[176:179], v141 offset:54272
	ds_read_b128 v[180:183], v141 offset:55296
	ds_read_b128 v[184:187], v141 offset:56320
	global_load_lds_dwordx4 v[208:209], off
	v_lshl_add_u64 v[206:207], v[206:207], 0, s[28:29]
	s_mov_b32 m0, s73
	s_nop 0
	global_load_lds_dwordx4 v[206:207], off
	s_barrier
	s_waitcnt lgkmcnt(0)
	s_waitcnt lgkmcnt(0)
	v_mfma_f32_16x16x32_f16 v[58:61], v[136:139], v[156:159], v[58:61]
	v_mfma_f32_16x16x32_f16 v[50:53], v[148:151], v[156:159], v[50:53]
	v_mfma_f32_16x16x32_f16 v[38:41], v[136:139], v[164:167], v[38:41]
	v_mfma_f32_16x16x32_f16 v[34:37], v[148:151], v[164:167], v[34:37]
	v_mfma_f32_16x16x32_f16 v[22:25], v[136:139], v[172:175], v[22:25]
	v_mfma_f32_16x16x32_f16 v[18:21], v[148:151], v[172:175], v[18:21]
	v_mfma_f32_16x16x32_f16 v[10:13], v[136:139], v[180:183], v[10:13]
	v_mfma_f32_16x16x32_f16 v[6:9], v[148:151], v[180:183], v[6:9]
	v_mfma_f32_16x16x32_f16 v[58:61], v[144:147], v[160:163], v[58:61]
	v_mfma_f32_16x16x32_f16 v[50:53], v[152:155], v[160:163], v[50:53]
	v_mfma_f32_16x16x32_f16 v[38:41], v[144:147], v[168:171], v[38:41]
	v_mfma_f32_16x16x32_f16 v[34:37], v[152:155], v[168:171], v[34:37]
	v_mfma_f32_16x16x32_f16 v[22:25], v[144:147], v[176:179], v[22:25]
	v_mfma_f32_16x16x32_f16 v[18:21], v[152:155], v[176:179], v[18:21]
	v_mfma_f32_16x16x32_f16 v[10:13], v[144:147], v[184:187], v[10:13]
	v_mfma_f32_16x16x32_f16 v[6:9], v[152:155], v[184:187], v[6:9]
	s_barrier
	s_mov_b32 m0, s74
	v_lshl_add_u64 v[136:137], v[204:205], 0, s[30:31]
	global_load_lds_dwordx4 v[136:137], off
	v_lshl_add_u64 v[136:137], v[204:205], 0, s[28:29]
	s_mov_b32 m0, s75
	s_nop 0
	global_load_lds_dwordx4 v[136:137], off
	s_waitcnt vmcnt(6)
	s_barrier
	v_mfma_f32_16x16x32_f16 v[62:65], v[188:191], v[156:159], v[62:65]
	v_mfma_f32_16x16x32_f16 v[70:73], v[196:199], v[156:159], v[70:73]
	v_mfma_f32_16x16x32_f16 v[42:45], v[188:191], v[164:167], v[42:45]
	v_mfma_f32_16x16x32_f16 v[46:49], v[196:199], v[164:167], v[46:49]
	v_mfma_f32_16x16x32_f16 v[26:29], v[188:191], v[172:175], v[26:29]
	v_mfma_f32_16x16x32_f16 v[30:33], v[196:199], v[172:175], v[30:33]
	v_mfma_f32_16x16x32_f16 v[14:17], v[188:191], v[180:183], v[14:17]
	v_mfma_f32_16x16x32_f16 v[2:5], v[196:199], v[180:183], v[2:5]
	v_mfma_f32_16x16x32_f16 v[62:65], v[192:195], v[160:163], v[62:65]
	v_mfma_f32_16x16x32_f16 v[70:73], v[200:203], v[160:163], v[70:73]
	v_mfma_f32_16x16x32_f16 v[42:45], v[192:195], v[168:171], v[42:45]
	v_mfma_f32_16x16x32_f16 v[46:49], v[200:203], v[168:171], v[46:49]
	v_mfma_f32_16x16x32_f16 v[26:29], v[192:195], v[176:179], v[26:29]
	v_mfma_f32_16x16x32_f16 v[30:33], v[200:203], v[176:179], v[30:33]
	v_mfma_f32_16x16x32_f16 v[14:17], v[192:195], v[184:187], v[14:17]
	v_mfma_f32_16x16x32_f16 v[2:5], v[200:203], v[184:187], v[2:5]
	s_add_i32 s85, s85, 2
	s_add_u32 s44, s44, 0x100
	s_addc_u32 s45, s45, 0
	s_add_u32 s51, s51, 0x100
	s_addc_u32 s84, s84, 0
	s_cmp_gt_u32 s85, 29
	s_barrier
	s_cbranch_scc1 .LBB0_846
